# v012 with the half-grid start offset of the in-proj phase reduced to ~7us
# speedup vs baseline: 1.0072x; 1.0040x over previous
.LBB0_207:
	s_or_b64 exec, exec, s[0:1]
	v_readlane_b32 s0, v247, 0
	v_readlane_b32 s1, v247, 1
	s_load_dwordx4 s[68:71], s[0:1], 0xc0
	v_readfirstlane_b32 s0, v184
	s_lshr_b32 s1, s0, 6
	v_bfe_u32 v2, v184, 5, 1
	v_lshrrev_b32_e32 v3, 1, v184
	s_waitcnt lgkmcnt(0)
	s_add_u32 s3, s70, 0x175100
	v_mov_b32_e32 v9, 0x3f2d8066
	v_mov_b32_e32 v10, 0x3fc45f30
	v_cmp_gt_u32_e64 s[44:45], 32, v207
	s_addc_u32 s33, s71, 0
	v_bfe_u32 v4, v184, 1, 3
	v_bitop3_b32 v3, v2, v3, 7 bitop3:0x78
	v_cndmask_b32_e64 v71, v9, v10, s[44:45]
	v_mov_b32_e32 v9, 0x912545c4
	v_mov_b32_e32 v10, 0x6dc9c883
	s_add_u32 s50, s70, 0x2b75100
	s_mulk_i32 s1, 0x3000
	v_and_b32_e32 v208, 7, v184
	v_lshlrev_b32_e32 v211, 4, v3
	v_bitop3_b32 v3, v2, v4, 2 bitop3:0x36
	v_mov_b32_e32 v67, 0
	v_cndmask_b32_e64 v70, v9, v10, s[44:45]
	v_mov_b32_e32 v9, 0x3f06e254
	v_mov_b32_e32 v10, 0x3f9f9ac0
	s_addc_u32 s51, s71, 0
	s_add_i32 s8, s1, 0x100
	s_and_b32 s6, s86, 7
	v_lshlrev_b32_e32 v212, 4, v3
	v_bitop3_b32 v3, v2, v4, 4 bitop3:0x36
	v_lshlrev_b32_e32 v186, 4, v208
	v_mov_b32_e32 v187, v67
	v_cndmask_b32_e64 v73, v9, v10, s[44:45]
	v_mov_b32_e32 v9, 0x3cfe9378
	v_mov_b32_e32 v10, 0x19d195e7
	s_cmp_lg_u32 s6, 0
	v_lshlrev_b32_e32 v213, 4, v3
	v_bitop3_b32 v3, v2, v4, 6 bitop3:0x36
	v_lshl_add_u64 v[4:5], s[70:71], 0, v[186:187]
	s_mov_b64 s[6:7], 0x4c75100
	v_cndmask_b32_e64 v72, v9, v10, s[44:45]
	v_mov_b32_e32 v9, 0x3ee1c040
	v_mov_b32_e32 v10, 0x3f7883ec
	s_cselect_b64 s[12:13], -1, 0
	s_and_b32 s56, s0, 64
	s_lshr_b32 s0, s0, 1
	v_lshl_add_u64 v[68:69], v[4:5], 0, s[6:7]
	v_and_b32_e32 v4, 15, v184
	v_cndmask_b32_e64 v75, v9, v10, s[44:45]
	v_mov_b32_e32 v9, 0xc4a3df88
	v_mov_b32_e32 v10, 0xe5870a9
	v_and_b32_e32 v189, 31, v184
	v_bfe_u32 v209, v184, 4, 2
	v_bfe_u32 v210, v184, 3, 3
	v_lshlrev_b32_e32 v214, 4, v3
	s_and_b32 s57, s0, 0x7fffffc0
	s_movk_i32 s0, 0x110
	v_mov_b32_e32 v3, s8
	v_lshlrev_b32_e32 v187, 4, v4
	v_cndmask_b32_e64 v74, v9, v10, s[44:45]
	v_mov_b32_e32 v9, 0x3ebb89df
	v_mov_b32_e32 v10, 0x3f53042d
	v_mad_u32_u24 v3, v189, s0, v3
	v_lshlrev_b32_e32 v6, 4, v2
	v_lshlrev_b32_e32 v2, 2, v2
	v_lshl_add_u32 v7, v208, 5, s8
	v_add_u32_e32 v5, s8, v187
	v_lshlrev_b32_e32 v188, 2, v4
	v_mul_u32_u24_e32 v4, 0x110, v210
	v_mul_u32_u24_e32 v8, 0x110, v209
	v_cndmask_b32_e64 v77, v9, v10, s[44:45]
	v_mov_b32_e32 v9, 0x4317ad85
	v_mov_b32_e32 v10, 0x185ebce3
	s_mov_b32 s1, 0
	s_ashr_i32 s52, s2, 3
	s_ashr_i32 s53, s86, 3
	s_bfe_u32 s54, s2, 0x10002
	s_and_b32 s55, s40, 24
	v_or_b32_e32 v90, 4, v209
	v_or_b32_e32 v91, 8, v209
	v_or_b32_e32 v92, 12, v209
	v_or_b32_e32 v93, 16, v209
	v_or_b32_e32 v94, 20, v209
	v_or_b32_e32 v95, 24, v209
	v_or_b32_e32 v96, 28, v209
	v_or_b32_e32 v97, 8, v210
	v_or_b32_e32 v98, 16, v210
	v_or_b32_e32 v99, 24, v210
	v_cndmask_b32_e64 v76, v9, v10, s[44:45]
	s_mov_b64 s[14:15], 0x20000
	s_mov_b64 s[16:17], 0x40000
	s_mov_b64 s[18:19], 0x60000
	s_mov_b64 s[20:21], 0x175180
	s_mov_b64 s[22:23], 0x195180
	s_mov_b64 s[24:25], 0x2b75180
	s_mov_b64 s[26:27], 0x2b95180
	s_mov_b64 s[28:29], 0x2bb5180
	s_mov_b64 s[30:31], 0x2bd5180
	s_movk_i32 s58, 0xa8
	s_mov_b32 s59, 0x2880000
	s_mov_b32 s60, 0x2080000
	s_mov_b32 s61, 0x1880000
	s_mov_b32 s62, 0x1080000
	v_mov_b32_e32 v100, 0x358637bd
	s_mov_b32 s63, 0x800000
	v_lshlrev_b32_e32 v66, 2, v2
	v_mbcnt_hi_u32_b32 v215, -1, v185
	v_add_u32_e32 v101, v3, v6
	v_add_u32_e32 v102, v5, v8
	v_mov_b32_e32 v103, 0x3e38aa3b
	v_add_u32_e32 v104, v7, v4
	v_mov_b32_e32 v105, 0x400
	s_mov_b32 s64, 0
	s_barrier
	s_cmp_lt_u32 s2, 0x80
	s_cbranch_scc1 .Lg1_nodelay
	s_movk_i32 s72, 2
